# hot loop headers aligned to 64 bytes (instruction-fetch alignment) on top of the P5 hoist version
# baseline (speedup 1.0000x reference)
.LBB0_268:
	ds_read_b128 v[162:165], v227 offset:36864
	ds_read_b128 v[166:169], v228 offset:55296
	ds_read_b128 v[230:233], v228 offset:59904
	s_mov_b64 s[28:29], 0x200
	s_add_i32 s20, s20, 2
	v_lshl_add_u64 v[208:209], v[208:209], 0, s[28:29]
	s_waitcnt lgkmcnt(1)
	v_mfma_f32_32x32x16_bf16 v[50:65], v[162:165], v[166:169], v[50:65]
	s_add_u32 s84, s84, s22
	s_addc_u32 s85, s85, s23
	s_add_u32 s86, s86, s22
	s_addc_u32 s87, s87, s23
	s_waitcnt lgkmcnt(0)
	v_mfma_f32_32x32x16_bf16 v[34:49], v[162:165], v[230:233], v[34:49]
	ds_read_b128 v[162:165], v227 offset:41472
	s_andn2_b64 vcc, exec, s[2:3]
	s_waitcnt lgkmcnt(0)
	v_mfma_f32_32x32x16_bf16 v[18:33], v[162:165], v[166:169], v[18:33]
	v_mfma_f32_32x32x16_bf16 v[2:17], v[162:165], v[230:233], v[2:17]
	ds_read_b128 v[162:165], v227 offset:36896
	ds_read_b128 v[166:169], v228 offset:55328
	ds_read_b128 v[230:233], v228 offset:59936
	s_waitcnt lgkmcnt(1)
	v_mfma_f32_32x32x16_bf16 v[50:65], v[162:165], v[166:169], v[50:65]
	s_waitcnt lgkmcnt(0)
	v_mfma_f32_32x32x16_bf16 v[34:49], v[162:165], v[230:233], v[34:49]
	ds_read_b128 v[162:165], v227 offset:41504
	s_waitcnt lgkmcnt(0)
	v_mfma_f32_32x32x16_bf16 v[18:33], v[162:165], v[166:169], v[18:33]
	v_mfma_f32_32x32x16_bf16 v[2:17], v[162:165], v[230:233], v[2:17]
	ds_read_b128 v[162:165], v227 offset:36928
	ds_read_b128 v[166:169], v228 offset:55360
	ds_read_b128 v[230:233], v228 offset:59968
	s_waitcnt lgkmcnt(1)
	v_mfma_f32_32x32x16_bf16 v[50:65], v[162:165], v[166:169], v[50:65]
	s_waitcnt lgkmcnt(0)
	v_mfma_f32_32x32x16_bf16 v[34:49], v[162:165], v[230:233], v[34:49]
	ds_read_b128 v[162:165], v227 offset:41536
	s_waitcnt lgkmcnt(0)
	v_mfma_f32_32x32x16_bf16 v[18:33], v[162:165], v[166:169], v[18:33]
	v_mfma_f32_32x32x16_bf16 v[2:17], v[162:165], v[230:233], v[2:17]
	ds_read_b128 v[162:165], v227 offset:36960
	ds_read_b128 v[166:169], v228 offset:55392
	ds_read_b128 v[230:233], v227 offset:41568
	ds_read_b128 v[234:237], v228 offset:60000
	s_waitcnt lgkmcnt(0)
	s_barrier
	v_mfma_f32_32x32x16_bf16 v[50:65], v[162:165], v[166:169], v[50:65]
	v_mfma_f32_32x32x16_bf16 v[34:49], v[162:165], v[234:237], v[34:49]
	v_mfma_f32_32x32x16_bf16 v[18:33], v[230:233], v[166:169], v[18:33]
	v_mfma_f32_32x32x16_bf16 v[2:17], v[230:233], v[234:237], v[2:17]
	s_cbranch_vccz .LBB0_289
	.p2align 6

.LBB0_674:
	ds_read_b128 v[162:165], v233 offset:55296
	ds_read_b128 v[166:169], v232 offset:36864
	ds_read_b128 v[234:237], v233 offset:59904
	s_mov_b64 s[22:23], 0x200
	s_add_i32 s14, s14, 2
	v_lshl_add_u64 v[194:195], v[194:195], 0, s[22:23]
	s_waitcnt lgkmcnt(1)
	v_mfma_f32_32x32x16_bf16 v[50:65], v[162:165], v[166:169], v[50:65]
	s_add_u32 s84, s84, s16
	s_addc_u32 s85, s85, s17
	s_add_u32 s86, s86, s16
	s_addc_u32 s87, s87, s17
	s_waitcnt lgkmcnt(0)
	v_mfma_f32_32x32x16_bf16 v[34:49], v[234:237], v[166:169], v[34:49]
	ds_read_b128 v[166:169], v232 offset:41472
	s_andn2_b64 vcc, exec, s[2:3]
	s_waitcnt lgkmcnt(0)
	v_mfma_f32_32x32x16_bf16 v[18:33], v[162:165], v[166:169], v[18:33]
	v_mfma_f32_32x32x16_bf16 v[2:17], v[234:237], v[166:169], v[2:17]
	ds_read_b128 v[162:165], v233 offset:55328
	ds_read_b128 v[166:169], v232 offset:36896
	ds_read_b128 v[234:237], v233 offset:59936
	s_waitcnt lgkmcnt(1)
	v_mfma_f32_32x32x16_bf16 v[50:65], v[162:165], v[166:169], v[50:65]
	s_waitcnt lgkmcnt(0)
	v_mfma_f32_32x32x16_bf16 v[34:49], v[234:237], v[166:169], v[34:49]
	ds_read_b128 v[166:169], v232 offset:41504
	s_waitcnt lgkmcnt(0)
	v_mfma_f32_32x32x16_bf16 v[18:33], v[162:165], v[166:169], v[18:33]
	v_mfma_f32_32x32x16_bf16 v[2:17], v[234:237], v[166:169], v[2:17]
	ds_read_b128 v[162:165], v233 offset:55360
	ds_read_b128 v[166:169], v232 offset:36928
	ds_read_b128 v[234:237], v233 offset:59968
	s_waitcnt lgkmcnt(1)
	v_mfma_f32_32x32x16_bf16 v[50:65], v[162:165], v[166:169], v[50:65]
	s_waitcnt lgkmcnt(0)
	v_mfma_f32_32x32x16_bf16 v[34:49], v[234:237], v[166:169], v[34:49]
	ds_read_b128 v[166:169], v232 offset:41536
	s_waitcnt lgkmcnt(0)
	v_mfma_f32_32x32x16_bf16 v[18:33], v[162:165], v[166:169], v[18:33]
	v_mfma_f32_32x32x16_bf16 v[2:17], v[234:237], v[166:169], v[2:17]
	ds_read_b128 v[162:165], v233 offset:55392
	ds_read_b128 v[166:169], v232 offset:36960
	ds_read_b128 v[234:237], v233 offset:60000
	ds_read_b128 v[238:241], v232 offset:41568
	s_waitcnt lgkmcnt(0)
	s_barrier
	v_mfma_f32_32x32x16_bf16 v[50:65], v[162:165], v[166:169], v[50:65]
	v_mfma_f32_32x32x16_bf16 v[34:49], v[234:237], v[166:169], v[34:49]
	v_mfma_f32_32x32x16_bf16 v[18:33], v[162:165], v[238:241], v[18:33]
	v_mfma_f32_32x32x16_bf16 v[2:17], v[234:237], v[238:241], v[2:17]
	s_cbranch_vccz .LBB0_621
	.p2align 6

.LBB0_945:
	s_or_b64 exec, exec, s[2:3]
	ds_read_u16 v1, v128 offset:13440
	ds_read_u16 v3, v131 offset:13584
	v_mov_b32_e32 v63, v51
	v_lshl_add_u64 v[4:5], v[4:5], 0, v[62:63]
	v_readlane_b32 s44, v245, 7
	v_readlane_b32 s46, v245, 9
	s_waitcnt lgkmcnt(0)
	v_lshl_or_b32 v6, v3, 16, v1
	ds_read_u16 v1, v131 offset:13728
	ds_read_u16 v3, v131 offset:13872
	s_mul_i32 s2, s46, 0x5000
	v_add_u32_e32 v120, s87, v120
	v_add_u32_e32 v154, s2, v154
	s_movk_i32 s2, 0x487f
	s_waitcnt lgkmcnt(0)
	v_lshl_or_b32 v7, v3, 16, v1
	v_mul_u32_u24_e32 v1, v2, v123
	v_lshlrev_b32_e32 v50, 1, v1
	v_lshl_add_u64 v[8:9], v[4:5], 0, v[50:51]
	global_store_dwordx2 v[8:9], v[6:7], off
	ds_read_u16 v1, v131 offset:13616
	ds_read_u16 v3, v131 offset:13472
	ds_read_u16 v10, v131 offset:13504
	v_cmp_lt_i32_e32 vcc, s2, v120
	s_or_b64 s[60:61], vcc, s[60:61]
	v_readlane_b32 s45, v245, 8
	s_waitcnt lgkmcnt(1)
	v_lshl_or_b32 v6, v1, 16, v3
	ds_read_u16 v1, v131 offset:13760
	ds_read_u16 v3, v131 offset:13904
	v_readlane_b32 s47, v245, 10
	s_waitcnt lgkmcnt(0)
	v_lshl_or_b32 v7, v3, 16, v1
	v_mul_u32_u24_e32 v1, v2, v134
	v_lshlrev_b32_e32 v50, 1, v1
	ds_read_u16 v1, v131 offset:13648
	v_lshl_add_u64 v[8:9], v[4:5], 0, v[50:51]
	global_store_dwordx2 v[8:9], v[6:7], off
	s_waitcnt lgkmcnt(0)
	v_lshl_or_b32 v6, v1, 16, v10
	ds_read_u16 v1, v131 offset:13792
	ds_read_u16 v3, v131 offset:13936
	s_waitcnt lgkmcnt(0)
	v_lshl_or_b32 v7, v3, 16, v1
	v_mul_u32_u24_e32 v1, v2, v135
	v_lshlrev_b32_e32 v50, 1, v1
	v_lshl_add_u64 v[8:9], v[4:5], 0, v[50:51]
	global_store_dwordx2 v[8:9], v[6:7], off
	ds_read_u16 v1, v131 offset:13536
	ds_read_u16 v3, v131 offset:13680
	s_waitcnt lgkmcnt(0)
	v_lshl_or_b32 v6, v3, 16, v1
	ds_read_u16 v1, v131 offset:13824
	ds_read_u16 v3, v131 offset:13968
	s_waitcnt lgkmcnt(0)
	v_lshl_or_b32 v7, v3, 16, v1
	v_mul_u32_u24_e32 v1, v2, v136
	v_lshlrev_b32_e32 v50, 1, v1
	v_lshl_add_u64 v[2:3], v[4:5], 0, v[50:51]
	global_store_dwordx2 v[2:3], v[6:7], off
	s_waitcnt lgkmcnt(0)
	s_andn2_b64 exec, exec, s[60:61]
	s_cbranch_execz .LBB0_1082
	.p2align 6

.LBB0_1493:
	s_or_saveexec_b64 s[0:1], s[0:1]
	v_mov_b64_e32 v[4:5], 0x10000
	s_xor_b64 exec, exec, s[0:1]
	v_mov_b32_e32 v147, 0
	v_lshl_add_u64 v[148:149], s[4:5], 0, v[146:147]
	v_mov_b64_e32 v[4:5], 0x9000
	v_mov_b32_e32 v8, v146
	s_or_b64 exec, exec, s[0:1]
	v_mov_b32_e32 v2, 0xe600000
	v_mov_b32_e32 v3, 0xc4c0000
	v_cndmask_b32_e32 v2, v2, v3, vcc
	v_mov_b32_e32 v3, 0
	v_lshl_add_u64 v[10:11], s[82:83], 0, v[2:3]
	v_mov_b32_e32 v135, 0x408000
	s_mov_b32 s3, 0
	v_mad_i64_i32 v[10:11], s[0:1], s6, v135, v[10:11]
	s_lshl_b32 s2, s7, 7
	v_lshlrev_b32_e32 v7, 8, v1
	v_lshl_add_u64 v[10:11], v[10:11], 0, s[2:3]
	v_and_b32_e32 v136, 0x7800, v7
	v_mov_b32_e32 v137, v3
	v_lshl_add_u64 v[10:11], v[10:11], 0, v[136:137]
	v_mov_b32_e32 v7, v3
	s_waitcnt vmcnt(0)
	v_lshl_add_u64 v[110:111], v[10:11], 0, v[6:7]
	v_mov_b32_e32 v9, 0x1bb06000
	v_mov_b32_e32 v10, 0x16b00000
	v_cndmask_b32_e32 v138, v9, v10, vcc
	v_mov_b32_e32 v139, v3
	v_lshl_add_u64 v[10:11], s[82:83], 0, v[138:139]
	v_mad_i64_i32 v[10:11], s[0:1], s6, v135, v[10:11]
	v_lshl_add_u64 v[10:11], v[10:11], 0, s[2:3]
	s_mov_b32 s0, 0x8000
	v_lshl_add_u64 v[10:11], v[10:11], 0, v[136:137]
	v_add_co_u32_e32 v18, vcc, s0, v110
	v_lshl_add_u64 v[114:115], v[10:11], 0, v[6:7]
	s_nop 0
	v_addc_co_u32_e32 v19, vcc, 0, v111, vcc
	v_and_b32_e32 v140, 0xf0, v8
	v_mov_b32_e32 v141, v3
	v_add_co_u32_e32 v22, vcc, s0, v114
	v_lshl_add_u64 v[126:127], s[4:5], 0, v[140:141]
	s_nop 0
	v_addc_co_u32_e32 v23, vcc, 0, v115, vcc
	s_mov_b32 s0, 0x9000
	v_add_co_u32_e32 v32, vcc, s0, v126
	v_lshl_add_u64 v[30:31], v[148:149], 0, v[4:5]
	s_nop 0
	v_addc_co_u32_e32 v33, vcc, 0, v127, vcc
	s_mov_b32 s0, 0x10000
	global_load_dwordx4 v[6:9], v[110:111], off
	global_load_dwordx4 v[10:13], v[114:115], off
	global_load_dwordx4 v[14:17], v[148:149], off
	s_nop 0
	global_load_dwordx4 v[18:21], v[18:19], off
	s_nop 0
	global_load_dwordx4 v[22:25], v[22:23], off
	s_nop 0
	global_load_dwordx4 v[26:29], v[30:31], off
	v_lshl_add_u64 v[58:59], v[30:31], 0, v[4:5]
	v_add_co_u32_e32 v30, vcc, s0, v110
	v_lshl_add_u64 v[62:63], v[58:59], 0, v[4:5]
	s_nop 0
	v_addc_co_u32_e32 v31, vcc, 0, v111, vcc
	v_add_co_u32_e32 v38, vcc, s0, v114
	s_mov_b32 s0, 0x12000
	s_nop 0
	v_addc_co_u32_e32 v39, vcc, 0, v115, vcc
	v_add_co_u32_e32 v46, vcc, s0, v126
	s_mov_b32 s0, 0x18000
	s_nop 0
	v_addc_co_u32_e32 v47, vcc, 0, v127, vcc
	v_add_co_u32_e32 v48, vcc, s0, v110
	global_load_dwordx4 v[34:37], v[32:33], off offset:2048
	s_nop 0
	v_addc_co_u32_e32 v49, vcc, 0, v111, vcc
	v_add_co_u32_e32 v50, vcc, s0, v114
	s_mov_b32 s0, 0x1b000
	s_nop 0
	v_addc_co_u32_e32 v51, vcc, 0, v115, vcc
	v_add_co_u32_e32 v64, vcc, s0, v126
	s_mov_b32 s0, 0x20000
	s_nop 0
	v_addc_co_u32_e32 v65, vcc, 0, v127, vcc
	global_load_dwordx4 v[30:33], v[30:31], off
	s_nop 0
	global_load_dwordx4 v[38:41], v[38:39], off
	s_nop 0
	global_load_dwordx4 v[42:45], v[58:59], off
	global_load_dwordx4 v[54:57], v[46:47], off offset:2048
	s_nop 0
	global_load_dwordx4 v[46:49], v[48:49], off
	v_lshl_add_u64 v[90:91], v[62:63], 0, v[4:5]
	global_load_dwordx4 v[58:61], v[62:63], off
	v_add_co_u32_e32 v62, vcc, s0, v110
	v_lshl_add_u64 v[106:107], v[90:91], 0, v[4:5]
	s_nop 0
	v_addc_co_u32_e32 v63, vcc, 0, v111, vcc
	v_add_co_u32_e32 v70, vcc, s0, v114
	s_mov_b32 s0, 0x24000
	s_nop 0
	v_addc_co_u32_e32 v71, vcc, 0, v115, vcc
	v_add_co_u32_e32 v78, vcc, s0, v126
	s_mov_b32 s0, 0x28000
	s_nop 0
	v_addc_co_u32_e32 v79, vcc, 0, v127, vcc
	v_add_co_u32_e32 v80, vcc, s0, v110
	v_lshl_add_u64 v[122:123], v[106:107], 0, v[4:5]
	s_nop 0
	v_addc_co_u32_e32 v81, vcc, 0, v111, vcc
	v_add_co_u32_e32 v82, vcc, s0, v114
	s_mov_b32 s0, 0x2d000
	s_nop 0
	v_addc_co_u32_e32 v83, vcc, 0, v115, vcc
	v_add_co_u32_e32 v94, vcc, s0, v126
	s_mov_b32 s0, 0x30000
	s_nop 0
	v_addc_co_u32_e32 v95, vcc, 0, v127, vcc
	v_add_co_u32_e32 v96, vcc, s0, v110
	global_load_dwordx4 v[50:53], v[50:51], off
	s_nop 0
	v_addc_co_u32_e32 v97, vcc, 0, v111, vcc
	v_add_co_u32_e32 v98, vcc, s0, v114
	s_mov_b32 s0, 0x36000
	s_nop 0
	v_addc_co_u32_e32 v99, vcc, 0, v115, vcc
	v_add_co_u32_e32 v112, vcc, s0, v126
	s_mov_b32 s0, 0x38000
	s_nop 0
	v_addc_co_u32_e32 v113, vcc, 0, v127, vcc
	v_add_co_u32_e32 v110, vcc, s0, v110
	global_load_dwordx4 v[66:69], v[64:65], off offset:2048
	s_nop 0
	v_addc_co_u32_e32 v111, vcc, 0, v111, vcc
	v_add_co_u32_e32 v114, vcc, s0, v114
	s_mov_b32 s0, 0x3f000
	s_nop 0
	v_addc_co_u32_e32 v115, vcc, 0, v115, vcc
	v_add_co_u32_e32 v130, vcc, s0, v126
	global_load_dwordx4 v[62:65], v[62:63], off
	s_nop 0
	global_load_dwordx4 v[70:73], v[70:71], off
	s_nop 0
	global_load_dwordx4 v[74:77], v[90:91], off
	global_load_dwordx4 v[86:89], v[78:79], off offset:2048
	s_nop 0
	global_load_dwordx4 v[78:81], v[80:81], off
	v_addc_co_u32_e32 v131, vcc, 0, v127, vcc
	global_load_dwordx4 v[82:85], v[82:83], off
	v_bfe_u32 v147, v1, 4, 2
	global_load_dwordx4 v[90:93], v[106:107], off
	global_load_dwordx4 v[102:105], v[94:95], off offset:2048
	s_nop 0
	global_load_dwordx4 v[94:97], v[96:97], off
	s_mul_i32 s9, s6, 0x408000
	global_load_dwordx4 v[106:109], v[122:123], off
	v_lshl_add_u64 v[122:123], v[122:123], 0, v[4:5]
	global_load_dwordx4 v[98:101], v[98:99], off
	s_nop 0
	global_load_dwordx4 v[118:121], v[112:113], off offset:2048
	s_nop 0
	global_load_dwordx4 v[110:113], v[110:111], off
	v_and_b32_e32 v5, 63, v1
	global_load_dwordx4 v[114:117], v[114:115], off
	v_lshlrev_b32_e32 v179, 4, v5
	global_load_dwordx4 v[122:125], v[122:123], off
	s_nop 0
	global_load_dwordx4 v[126:129], v140, s[4:5] offset:2048
	s_nop 0
	global_load_dwordx4 v[130:133], v[130:131], off offset:2048
	s_add_i32 s4, s8, s7
	s_mul_hi_i32 s5, s4, 0x900
	s_mulk_i32 s4, 0x900
	v_or_b32_e32 v150, s4, v140
	v_mov_b32_e32 v151, s5
	v_mad_i64_i32 v[156:157], s[4:5], s6, v135, v[2:3]
	v_readlane_b32 s4, v245, 0
	s_lshl_b32 s4, s4, 7
	v_and_b32_e32 v5, 7, v1
	v_or_b32_e32 v2, v156, v136
	v_readlane_b32 s5, v245, 1
	s_and_b32 s7, s4, 0x780
	v_lshlrev_b32_e32 v5, 4, v5
	v_sub_u32_e32 v180, 0, v134
	v_sub_u32_e32 v181, v146, v134
	v_or3_b32 v156, v2, s7, v5
	v_mad_i64_i32 v[134:135], s[4:5], s6, v135, v[138:139]
	v_lshl_or_b32 v2, v147, 13, s9
	s_mul_hi_i32 s2, s6, 0x408000
	v_mul_hi_u32_u24_e32 v153, 15, v4
	v_mul_u32_u24_e32 v152, 15, v4
	v_lshlrev_b32_e32 v154, 3, v4
	v_lshl_add_u64 v[158:159], v[134:135], 0, v[136:137]
	v_mul_hi_u32_u24_e32 v161, 14, v4
	v_mul_u32_u24_e32 v160, 14, v4
	v_mul_hi_u32_u24_e32 v163, 13, v4
	v_mul_u32_u24_e32 v162, 13, v4
	v_mul_hi_u32_u24_e32 v165, 12, v4
	v_mul_u32_u24_e32 v164, 12, v4
	v_mul_hi_u32_u24_e32 v167, 11, v4
	v_mul_u32_u24_e32 v166, 11, v4
	v_mul_hi_u32_u24_e32 v169, 10, v4
	v_mul_u32_u24_e32 v168, 10, v4
	v_mul_hi_u32_u24_e32 v171, 9, v4
	v_mul_u32_u24_e32 v170, 9, v4
	v_or_b32_e32 v4, s7, v2
	v_lshrrev_b32_e32 v2, 1, v1
	v_or3_b32 v158, v158, s7, v5
	v_mov_b32_e32 v5, s2
	v_and_b32_e32 v2, 0x1e0, v2
	v_lshl_add_u64 v[172:173], v[4:5], 0, v[2:3]
	v_mov_b32_e32 v4, v3
	v_mov_b32_e32 v5, v3
	v_and_b32_e32 v178, 15, v1
	v_mov_b32_e32 v2, v3
	v_mov_b64_e32 v[136:137], v[4:5]
	v_mov_b64_e32 v[140:141], v[4:5]
	v_mov_b64_e32 v[144:145], v[4:5]
	v_cmp_gt_u32_e64 s[0:1], 16, v1
	v_and_b32_e32 v182, 48, v1
	v_mov_b32_e32 v155, v3
	v_lshl_or_b32 v172, v178, 1, v172
	s_mov_b32 s2, 0xa380000
	s_mov_b32 s12, 0xa388000
	s_mov_b32 s13, 0xa390000
	s_mov_b32 s16, 0xa398000
	s_mov_b32 s17, 0xa3a0000
	s_mov_b32 s18, 0xa3a8000
	s_mov_b32 s19, 0xa3b0000
	s_mov_b32 s20, 0xa3b8000
	s_mov_b64 s[4:5], 0x48000
	s_mov_b64 s[6:7], 0x40000
	v_mov_b64_e32 v[134:135], v[2:3]
	v_mov_b64_e32 v[138:139], v[2:3]
	v_mov_b64_e32 v[142:143], v[2:3]
	.p2align 6

.LBB0_1611:
	v_lshrrev_b32_e32 v2, 6, v1
	v_readlane_b32 s2, v245, 0
	v_readlane_b32 s3, v245, 1
	s_nop 0
	v_lshl_add_u32 v3, s2, 2, v2
	s_mov_b32 s2, 0x8500
	v_cmp_gt_i32_e32 vcc, s2, v3
	s_and_saveexec_b64 s[2:3], vcc
	s_cbranch_execz .LBB0_1614
	v_and_b32_e32 v2, 63, v1
	v_bfe_u32 v4, v1, 6, 1
	s_add_u32 s4, s82, 0xa380000
	v_lshlrev_b32_e32 v2, 3, v2
	v_mov_b32_e32 v9, 0
	v_lshlrev_b32_e32 v8, 5, v4
	v_lshrrev_b32_e32 v1, 1, v1
	s_addc_u32 s5, s83, 0
	v_lshl_or_b32 v2, v4, 9, v2
	v_lshl_add_u64 v[4:5], s[82:83], 0, v[8:9]
	v_and_b32_e32 v8, 28, v1
	v_readlane_b32 s16, v245, 44
	s_add_u32 s6, s82, 0x10740000
	v_lshl_add_u64 v[4:5], v[4:5], 0, v[8:9]
	v_lshlrev_b32_e32 v8, 2, v2
	v_readlane_b32 s17, v245, 45
	v_readlane_b32 s18, v245, 46
	v_readlane_b32 s19, v245, 47
	v_readlane_b32 s20, v245, 48
	v_readlane_b32 s21, v245, 49
	v_readlane_b32 s22, v245, 50
	v_readlane_b32 s23, v245, 51
	v_readlane_b32 s24, v245, 52
	v_readlane_b32 s25, v245, 53
	v_readlane_b32 s26, v245, 54
	v_readlane_b32 s27, v245, 55
	v_readlane_b32 s28, v245, 56
	v_readlane_b32 s29, v245, 57
	v_readlane_b32 s30, v245, 58
	v_readlane_b32 s31, v245, 59
	s_addc_u32 s7, s83, 0
	v_readlane_b32 s12, v245, 7
	v_lshl_add_u64 v[6:7], s[30:31], 0, v[8:9]
	v_readlane_b32 s16, v245, 60
	s_add_u32 s8, s82, 0x18c40000
	v_readlane_b32 s13, v245, 8
	v_readlane_b32 s14, v245, 9
	s_mov_b64 s[10:11], 0x1b9fc000
	v_readlane_b32 s17, v245, 61
	s_addc_u32 s9, s83, 0
	s_lshl_b32 s12, s14, 2
	v_lshl_add_u64 v[4:5], v[4:5], 0, s[10:11]
	v_lshl_add_u64 v[8:9], s[16:17], 0, v[8:9]
	s_mov_b64 s[10:11], 0
	v_mov_b32_e32 v1, 0x3a27c5ac
	s_mov_b32 s13, 0x800000
	s_mov_b32 s14, 0x84ff
	v_readlane_b32 s15, v245, 10
	v_readlane_b32 s18, v245, 62
	v_readlane_b32 s19, v245, 63
	v_readlane_b32 s20, v244, 0
	v_readlane_b32 s21, v244, 1
	v_readlane_b32 s22, v244, 2
	v_readlane_b32 s23, v244, 3
	v_readlane_b32 s24, v244, 4
	v_readlane_b32 s25, v244, 5
	v_readlane_b32 s26, v244, 6
	v_readlane_b32 s27, v244, 7
	v_readlane_b32 s28, v244, 8
	v_readlane_b32 s29, v244, 9
	v_readlane_b32 s30, v244, 10
	v_readlane_b32 s31, v244, 11
	global_load_dwordx4 v[236:239], v[6:7], off offset:16
	global_load_dwordx4 v[232:235], v[6:7], off
	global_load_dwordx4 v[246:249], v[8:9], off offset:16
	global_load_dwordx4 v[240:243], v[8:9], off
	.p2align 6

.LBB0_1723:
	s_add_i32 s37, s37, 2
	s_add_u32 s84, s84, s18
	s_addc_u32 s85, s85, s19
	s_add_u32 s86, s86, s18
	s_addc_u32 s87, s87, s19
	s_andn2_b64 vcc, exec, s[20:21]
	s_waitcnt lgkmcnt(4)
	v_mfma_f32_32x32x16_bf16 v[50:65], v[192:195], v[196:199], v[50:65]
	v_mfma_f32_32x32x16_bf16 v[34:49], v[192:195], v[200:203], v[34:49]
	v_mfma_f32_32x32x16_bf16 v[18:33], v[204:207], v[196:199], v[18:33]
	v_mfma_f32_32x32x16_bf16 v[2:17], v[204:207], v[200:203], v[2:17]
	ds_read_b128 v[164:167], v161 offset:36928
	ds_read_b128 v[168:171], v162 offset:55360
	ds_read_b128 v[172:175], v162 offset:59968
	ds_read_b128 v[176:179], v161 offset:41536
	s_waitcnt lgkmcnt(4)
	v_mfma_f32_32x32x16_bf16 v[50:65], v[208:211], v[212:215], v[50:65]
	v_mfma_f32_32x32x16_bf16 v[34:49], v[208:211], v[216:219], v[34:49]
	v_mfma_f32_32x32x16_bf16 v[18:33], v[220:223], v[212:215], v[18:33]
	v_mfma_f32_32x32x16_bf16 v[2:17], v[220:223], v[216:219], v[2:17]
	ds_read_b128 v[180:183], v161 offset:36960
	ds_read_b128 v[184:187], v162 offset:55392
	ds_read_b128 v[188:191], v162 offset:60000
	ds_read_b128 v[224:227], v161 offset:41568
	s_waitcnt lgkmcnt(4)
	v_mfma_f32_32x32x16_bf16 v[50:65], v[164:167], v[168:171], v[50:65]
	v_mfma_f32_32x32x16_bf16 v[34:49], v[164:167], v[172:175], v[34:49]
	s_waitcnt lgkmcnt(0)
	s_barrier
	ds_read_b128 v[192:195], v161 offset:0
	ds_read_b128 v[196:199], v162 offset:18432
	ds_read_b128 v[200:203], v162 offset:23040
	ds_read_b128 v[204:207], v161 offset:4608
	ds_read_b128 v[208:211], v161 offset:32
	ds_read_b128 v[212:215], v162 offset:18464
	ds_read_b128 v[216:219], v162 offset:23072
	ds_read_b128 v[220:223], v161 offset:4640
	v_mfma_f32_32x32x16_bf16 v[18:33], v[176:179], v[168:171], v[18:33]
	v_mfma_f32_32x32x16_bf16 v[2:17], v[176:179], v[172:175], v[2:17]
	v_mfma_f32_32x32x16_bf16 v[50:65], v[180:183], v[184:187], v[50:65]
	v_mfma_f32_32x32x16_bf16 v[34:49], v[180:183], v[188:191], v[34:49]
	v_mfma_f32_32x32x16_bf16 v[18:33], v[224:227], v[184:187], v[18:33]
	v_mfma_f32_32x32x16_bf16 v[2:17], v[224:227], v[188:191], v[2:17]
	s_cbranch_vccz .LBB0_1682
	.p2align 6

.LBB0_1922:
	s_add_i32 s35, s35, 2
	s_add_u32 s84, s84, s30
	s_addc_u32 s85, s85, s31
	s_add_u32 s86, s86, s30
	s_addc_u32 s87, s87, s31
	s_andn2_b64 vcc, exec, s[2:3]
	s_waitcnt lgkmcnt(4)
	v_mfma_f32_32x32x16_bf16 v[50:65], v[206:209], v[210:213], v[50:65]
	v_mfma_f32_32x32x16_bf16 v[34:49], v[206:209], v[214:217], v[34:49]
	v_mfma_f32_32x32x16_bf16 v[18:33], v[218:221], v[210:213], v[18:33]
	v_mfma_f32_32x32x16_bf16 v[2:17], v[218:221], v[214:217], v[2:17]
	ds_read_b128 v[206:209], v203 offset:36928
	ds_read_b128 v[210:213], v204 offset:55360
	ds_read_b128 v[214:217], v204 offset:59968
	ds_read_b128 v[218:221], v203 offset:41536
	s_waitcnt lgkmcnt(4)
	v_mfma_f32_32x32x16_bf16 v[50:65], v[222:225], v[226:229], v[50:65]
	v_mfma_f32_32x32x16_bf16 v[34:49], v[222:225], v[230:233], v[34:49]
	v_mfma_f32_32x32x16_bf16 v[18:33], v[234:237], v[226:229], v[18:33]
	v_mfma_f32_32x32x16_bf16 v[2:17], v[234:237], v[230:233], v[2:17]
	ds_read_b128 v[222:225], v203 offset:36960
	ds_read_b128 v[226:229], v204 offset:55392
	ds_read_b128 v[230:233], v204 offset:60000
	ds_read_b128 v[234:237], v203 offset:41568
	s_waitcnt lgkmcnt(4)
	v_mfma_f32_32x32x16_bf16 v[50:65], v[206:209], v[210:213], v[50:65]
	v_mfma_f32_32x32x16_bf16 v[34:49], v[206:209], v[214:217], v[34:49]
	s_waitcnt lgkmcnt(0)
	s_barrier
	v_mfma_f32_32x32x16_bf16 v[18:33], v[218:221], v[210:213], v[18:33]
	v_mfma_f32_32x32x16_bf16 v[2:17], v[218:221], v[214:217], v[2:17]
	ds_read_b128 v[206:209], v203 offset:0
	ds_read_b128 v[210:213], v204 offset:18432
	ds_read_b128 v[214:217], v204 offset:23040
	ds_read_b128 v[218:221], v203 offset:4608
	v_mfma_f32_32x32x16_bf16 v[50:65], v[222:225], v[226:229], v[50:65]
	v_mfma_f32_32x32x16_bf16 v[34:49], v[222:225], v[230:233], v[34:49]
	v_mfma_f32_32x32x16_bf16 v[18:33], v[234:237], v[226:229], v[18:33]
	v_mfma_f32_32x32x16_bf16 v[2:17], v[234:237], v[230:233], v[2:17]
	ds_read_b128 v[222:225], v203 offset:32
	ds_read_b128 v[226:229], v204 offset:18464
	ds_read_b128 v[230:233], v204 offset:23072
	ds_read_b128 v[234:237], v203 offset:4640
	s_cbranch_vccz .LBB0_1943
	.p2align 6

.LBB0_2098:
	v_ashrrev_i32_e32 v5, 31, v4
	v_lshlrev_b64 v[54:55], 10, v[4:5]
	v_lshl_add_u64 v[4:5], s[18:19], 0, v[54:55]
	v_lshl_add_u64 v[6:7], v[4:5], 0, v[52:53]
	global_load_dword v8, v[6:7], off
	global_load_dword v10, v[6:7], off offset:256
	v_lshl_add_u64 v[4:5], v[4:5], 0, v[50:51]
	global_load_dword v117, v[4:5], off
	global_load_dword v119, v[6:7], off offset:512
	global_load_dword v120, v[6:7], off offset:768
	global_load_dword v118, v[4:5], off offset:256
	v_cmp_lt_u32_e32 vcc, v116, v115
	v_mov_b32_e32 v129, 0
	v_mov_b32_e32 v128, 0
	s_waitcnt vmcnt(5)
	v_ashrrev_i32_e32 v9, 31, v8
	s_waitcnt vmcnt(4)
	v_ashrrev_i32_e32 v11, 31, v10
	v_lshlrev_b64 v[4:5], 2, v[8:9]
	v_lshlrev_b64 v[6:7], 2, v[10:11]
	v_lshl_add_u64 v[8:9], s[20:21], 0, v[4:5]
	v_lshl_add_u64 v[10:11], s[20:21], 0, v[6:7]
	v_lshl_add_u64 v[4:5], s[22:23], 0, v[4:5]
	v_lshl_add_u64 v[6:7], s[22:23], 0, v[6:7]
	global_load_dword v123, v[8:9], off
	global_load_dword v3, v[10:11], off
	global_load_dword v121, v[4:5], off
	global_load_dword v122, v[6:7], off
	s_and_saveexec_b64 s[26:27], vcc
	s_cbranch_execz .LBB0_2102
	v_lshl_add_u64 v[4:5], v[54:55], 1, v[36:37]
	global_load_dwordx4 v[8:11], v[4:5], off
	global_load_dwordx4 v[16:19], v[4:5], off offset:16
	v_cmp_lt_i32_e64 s[12:13], v110, v111
	v_lshrrev_b32_e32 v124, 4, v116
	v_mov_b32_e32 v129, 0
	v_cndmask_b32_e64 v4, v109, v110, s[12:13]
	v_cmp_lt_i32_e64 s[12:13], v112, v111
	s_mov_b64 s[28:29], 0
	v_mov_b32_e32 v128, 0
	v_cndmask_b32_e64 v5, v109, v112, s[12:13]
	v_lshlrev_b32_e32 v125, 2, v4
	v_lshlrev_b32_e32 v126, 2, v5
	v_mov_b32_e32 v127, v116
	s_waitcnt vmcnt(1)
	v_lshlrev_b32_e32 v4, 16, v8
	v_and_b32_e32 v5, 0xffff0000, v8
	v_lshlrev_b32_e32 v6, 16, v9
	v_and_b32_e32 v7, 0xffff0000, v9
	v_lshlrev_b32_e32 v8, 16, v10
	v_and_b32_e32 v9, 0xffff0000, v10
	v_lshlrev_b32_e32 v10, 16, v11
	v_and_b32_e32 v11, 0xffff0000, v11
	s_waitcnt vmcnt(0)
	v_lshlrev_b32_e32 v12, 16, v16
	v_and_b32_e32 v13, 0xffff0000, v16
	v_lshlrev_b32_e32 v14, 16, v17
	v_and_b32_e32 v15, 0xffff0000, v17
	v_lshlrev_b32_e32 v16, 16, v18
	v_and_b32_e32 v17, 0xffff0000, v18
	v_lshlrev_b32_e32 v18, 16, v19
	v_and_b32_e32 v19, 0xffff0000, v19
	.p2align 6

.LBB0_2108:
	s_andn2_saveexec_b64 s[2:3], s[2:3]
	v_mul_f32_e32 v3, v60, v60
	v_fmamk_f32 v4, v3, 0xba1345e1, v43
	v_fmaak_f32 v4, v3, v4, 0xbcdac9b8
	v_fmaak_f32 v4, v3, v4, 0x3de703be
	v_fmaak_f32 v4, v3, v4, 0xbec09330
	v_fmaak_f32 v3, v3, v4, 0x3e0375d0
	v_fma_f32 v61, |v60|, v3, |v60|
	s_or_b64 exec, exec, s[2:3]
	v_mov_b32_e32 v16, v2
	v_mov_b32_e32 v17, v2
	v_mov_b32_e32 v3, v2
	v_mov_b32_e32 v4, v2
	v_mov_b32_e32 v5, v2
	v_mov_b32_e32 v6, v2
	v_mov_b32_e32 v7, v2
	v_mov_b32_e32 v8, v2
	v_mov_b32_e32 v9, v2
	v_mov_b32_e32 v10, v2
	v_mov_b32_e32 v11, v2
	v_mov_b32_e32 v12, v2
	v_mov_b32_e32 v13, v2
	v_mov_b32_e32 v14, v2
	v_mov_b32_e32 v15, v2
	v_mov_b32_e32 v19, 0
	v_mov_b64_e32 v[34:35], v[16:17]
	v_mov_b32_e32 v18, v19
	v_mov_b64_e32 v[32:33], v[14:15]
	v_mov_b64_e32 v[30:31], v[12:13]
	v_mov_b64_e32 v[28:29], v[10:11]
	v_mov_b64_e32 v[26:27], v[8:9]
	v_mov_b64_e32 v[24:25], v[6:7]
	v_mov_b64_e32 v[22:23], v[4:5]
	v_mov_b64_e32 v[20:21], v[2:3]
	s_and_saveexec_b64 s[12:13], vcc
	s_cbranch_execz .LBB0_2115
	v_bfi_b32 v4, s46, v61, v60
	v_mul_f32_e32 v3, 0.5, v59
	v_add_f32_e32 v4, 1.0, v4
	v_bfi_b32 v5, s46, v58, v57
	v_mul_f32_e32 v3, v3, v4
	v_mul_f32_e32 v4, 0.5, v56
	v_add_f32_e32 v5, 1.0, v5
	v_mul_f32_e32 v4, v4, v5
	v_mul_f32_e32 v3, v120, v3
	v_mul_f32_e32 v4, v119, v4
	v_mov_b32_e32 v18, 0
	s_waitcnt vmcnt(0)
	v_mul_f32_e32 v3, v122, v3
	v_mul_f32_e32 v119, v121, v4
	s_mov_b64 s[14:15], 0
	v_mov_b32_e32 v19, v18
	v_mov_b32_e32 v4, v18
	v_mov_b32_e32 v5, v18
	v_mov_b32_e32 v6, v18
	v_mov_b32_e32 v7, v18
	v_mov_b32_e32 v8, v18
	v_mov_b32_e32 v9, v18
	v_mov_b32_e32 v10, v18
	v_mov_b32_e32 v11, v18
	v_mov_b32_e32 v12, v18
	v_mov_b32_e32 v13, v18
	v_mov_b32_e32 v14, v18
	v_mov_b32_e32 v15, v18
	v_mov_b32_e32 v16, v18
	v_mov_b32_e32 v17, v18
	.p2align 6

.LBB0_2252:
	s_add_i32 s13, s13, 2
	s_add_u32 s84, s84, s22
	s_addc_u32 s85, s85, s23
	s_add_u32 s86, s86, s22
	s_addc_u32 s87, s87, s23
	s_andn2_b64 vcc, exec, s[2:3]
	s_waitcnt lgkmcnt(4)
	v_mfma_f32_32x32x16_bf16 v[50:65], v[212:215], v[216:219], v[50:65]
	v_mfma_f32_32x32x16_bf16 v[34:49], v[220:223], v[216:219], v[34:49]
	v_mfma_f32_32x32x16_bf16 v[18:33], v[212:215], v[224:227], v[18:33]
	v_mfma_f32_32x32x16_bf16 v[2:17], v[220:223], v[224:227], v[2:17]
	ds_read_b128 v[184:187], v182 offset:55360
	ds_read_b128 v[188:191], v162 offset:36928
	ds_read_b128 v[192:195], v182 offset:59968
	ds_read_b128 v[196:199], v162 offset:41536
	s_waitcnt lgkmcnt(4)
	v_mfma_f32_32x32x16_bf16 v[50:65], v[228:231], v[232:235], v[50:65]
	v_mfma_f32_32x32x16_bf16 v[34:49], v[236:239], v[232:235], v[34:49]
	v_mfma_f32_32x32x16_bf16 v[18:33], v[228:231], v[240:243], v[18:33]
	v_mfma_f32_32x32x16_bf16 v[2:17], v[236:239], v[240:243], v[2:17]
	ds_read_b128 v[200:203], v182 offset:55392
	ds_read_b128 v[204:207], v162 offset:36960
	ds_read_b128 v[208:211], v182 offset:60000
	ds_read_b128 v[248:251], v162 offset:41568
	s_waitcnt lgkmcnt(4)
	v_mfma_f32_32x32x16_bf16 v[50:65], v[184:187], v[188:191], v[50:65]
	v_mfma_f32_32x32x16_bf16 v[34:49], v[192:195], v[188:191], v[34:49]
	s_waitcnt lgkmcnt(0)
	s_barrier
	ds_read_b128 v[212:215], v182 offset:18432
	ds_read_b128 v[216:219], v162 offset:0
	ds_read_b128 v[220:223], v182 offset:23040
	ds_read_b128 v[224:227], v162 offset:4608
	ds_read_b128 v[228:231], v182 offset:18464
	ds_read_b128 v[232:235], v162 offset:32
	ds_read_b128 v[236:239], v182 offset:23072
	ds_read_b128 v[240:243], v162 offset:4640
	v_mfma_f32_32x32x16_bf16 v[18:33], v[184:187], v[196:199], v[18:33]
	v_mfma_f32_32x32x16_bf16 v[2:17], v[192:195], v[196:199], v[2:17]
	v_mfma_f32_32x32x16_bf16 v[50:65], v[200:203], v[204:207], v[50:65]
	v_mfma_f32_32x32x16_bf16 v[34:49], v[208:211], v[204:207], v[34:49]
	v_mfma_f32_32x32x16_bf16 v[18:33], v[200:203], v[248:251], v[18:33]
	v_mfma_f32_32x32x16_bf16 v[2:17], v[208:211], v[248:251], v[2:17]
	s_cbranch_vccz .LBB0_2265
	.p2align 6

.LBB0_2665:
	s_or_b64 exec, exec, s[92:93]
	ds_read_b32 v66, v206
	s_add_i32 s96, s96, 64
	s_and_b64 vcc, exec, s[90:91]
	s_waitcnt lgkmcnt(0)
	v_mul_f32_e32 v66, 0x3fb8aa3b, v66
	v_exp_f32_e32 v82, v66
	ds_read_b128 v[234:237], v208 offset:34816
	ds_read_b128 v[66:69], v159 offset:62464
	ds_read_b128 v[238:241], v208 offset:34848
	ds_read_b128 v[70:73], v159 offset:62496
	ds_read_b128 v[246:249], v208 offset:34880
	ds_read_b128 v[74:77], v159 offset:62528
	ds_read_b128 v[250:253], v208 offset:34912
	ds_read_b128 v[78:81], v159 offset:62560
	ds_read_b128 v[84:87], v208 offset:39424
	v_pk_mul_f32 v[64:65], v[64:65], v[82:83] op_sel_hi:[1,0]
	v_pk_mul_f32 v[62:63], v[62:63], v[82:83] op_sel_hi:[1,0]
	v_pk_mul_f32 v[60:61], v[60:61], v[82:83] op_sel_hi:[1,0]
	v_pk_mul_f32 v[58:59], v[58:59], v[82:83] op_sel_hi:[1,0]
	v_pk_mul_f32 v[56:57], v[56:57], v[82:83] op_sel_hi:[1,0]
	v_pk_mul_f32 v[54:55], v[54:55], v[82:83] op_sel_hi:[1,0]
	v_pk_mul_f32 v[52:53], v[52:53], v[82:83] op_sel_hi:[1,0]
	v_pk_mul_f32 v[50:51], v[50:51], v[82:83] op_sel_hi:[1,0]
	v_pk_mul_f32 v[48:49], v[48:49], v[82:83] op_sel_hi:[1,0]
	v_pk_mul_f32 v[46:47], v[46:47], v[82:83] op_sel_hi:[1,0]
	s_waitcnt lgkmcnt(7)
	v_mfma_f32_32x32x16_bf16 v[50:65], v[234:237], v[66:69], v[50:65]
	ds_read_b128 v[234:237], v208 offset:39456
	v_mul_f32_e64 v44, v44, v82
	v_mul_f32_e64 v45, v45, v82
	v_mul_f32_e64 v42, v42, v82
	v_mul_f32_e64 v43, v43, v82
	v_mul_f32_e64 v40, v40, v82
	v_mul_f32_e64 v41, v41, v82
	v_pk_mul_f32 v[38:39], v[38:39], v[82:83] op_sel_hi:[1,0]
	v_pk_mul_f32 v[36:37], v[36:37], v[82:83] op_sel_hi:[1,0]
	v_pk_mul_f32 v[34:35], v[34:35], v[82:83] op_sel_hi:[1,0]
	v_pk_mul_f32 v[32:33], v[32:33], v[82:83] op_sel_hi:[1,0]
	s_waitcnt lgkmcnt(6)
	v_mfma_f32_32x32x16_bf16 v[50:65], v[238:241], v[70:73], v[50:65]
	ds_read_b128 v[238:241], v208 offset:39488
	v_mul_f32_e64 v30, v30, v82
	v_mul_f32_e64 v31, v31, v82
	v_mul_f32_e64 v28, v28, v82
	v_mul_f32_e64 v29, v29, v82
	v_pk_mul_f32 v[26:27], v[26:27], v[82:83] op_sel_hi:[1,0]
	v_pk_mul_f32 v[24:25], v[24:25], v[82:83] op_sel_hi:[1,0]
	v_pk_mul_f32 v[22:23], v[22:23], v[82:83] op_sel_hi:[1,0]
	v_pk_mul_f32 v[20:21], v[20:21], v[82:83] op_sel_hi:[1,0]
	s_waitcnt lgkmcnt(5)
	v_mfma_f32_32x32x16_bf16 v[50:65], v[246:249], v[74:77], v[50:65]
	ds_read_b128 v[246:249], v208 offset:39520
	v_mul_f32_e64 v18, v18, v82
	v_mul_f32_e64 v19, v19, v82
	v_mul_f32_e64 v16, v16, v82
	v_mul_f32_e64 v17, v17, v82
	v_pk_mul_f32 v[14:15], v[14:15], v[82:83] op_sel_hi:[1,0]
	v_pk_mul_f32 v[12:13], v[12:13], v[82:83] op_sel_hi:[1,0]
	v_pk_mul_f32 v[10:11], v[10:11], v[82:83] op_sel_hi:[1,0]
	v_pk_mul_f32 v[8:9], v[8:9], v[82:83] op_sel_hi:[1,0]
	s_waitcnt lgkmcnt(4)
	v_mfma_f32_32x32x16_bf16 v[50:65], v[250:253], v[78:81], v[50:65]
	ds_read_b128 v[250:253], v208 offset:44032
	v_mul_f32_e64 v6, v6, v82
	v_mul_f32_e64 v7, v7, v82
	v_mul_f32_e64 v4, v4, v82
	v_mul_f32_e64 v5, v5, v82
	v_pk_mul_f32 v[2:3], v[2:3], v[82:83] op_sel_hi:[1,0]
	s_waitcnt lgkmcnt(4)
	v_mfma_f32_32x32x16_bf16 v[34:49], v[84:87], v[66:69], v[34:49]
	ds_read_b128 v[84:87], v208 offset:44064
	s_waitcnt lgkmcnt(4)
	v_mfma_f32_32x32x16_bf16 v[34:49], v[234:237], v[70:73], v[34:49]
	ds_read_b128 v[234:237], v208 offset:44096
	s_waitcnt lgkmcnt(4)
	v_mfma_f32_32x32x16_bf16 v[34:49], v[238:241], v[74:77], v[34:49]
	ds_read_b128 v[238:241], v208 offset:44128
	s_waitcnt lgkmcnt(4)
	v_mfma_f32_32x32x16_bf16 v[34:49], v[246:249], v[78:81], v[34:49]
	ds_read_b128 v[246:249], v208 offset:48640
	s_waitcnt lgkmcnt(4)
	v_mfma_f32_32x32x16_bf16 v[18:33], v[250:253], v[66:69], v[18:33]
	ds_read_b128 v[250:253], v208 offset:48672
	s_waitcnt lgkmcnt(4)
	v_mfma_f32_32x32x16_bf16 v[18:33], v[84:87], v[70:73], v[18:33]
	ds_read_b128 v[84:87], v208 offset:48704
	s_waitcnt lgkmcnt(4)
	v_mfma_f32_32x32x16_bf16 v[18:33], v[234:237], v[74:77], v[18:33]
	ds_read_b128 v[234:237], v208 offset:48736
	s_waitcnt lgkmcnt(4)
	v_mfma_f32_32x32x16_bf16 v[18:33], v[238:241], v[78:81], v[18:33]
	s_waitcnt lgkmcnt(3)
	v_mfma_f32_32x32x16_bf16 v[2:17], v[246:249], v[66:69], v[2:17]
	s_waitcnt lgkmcnt(2)
	v_mfma_f32_32x32x16_bf16 v[2:17], v[250:253], v[70:73], v[2:17]
	s_waitcnt lgkmcnt(1)
	v_mfma_f32_32x32x16_bf16 v[2:17], v[84:87], v[74:77], v[2:17]
	s_waitcnt lgkmcnt(0)
	s_barrier
	v_mfma_f32_32x32x16_bf16 v[2:17], v[234:237], v[78:81], v[2:17]
	s_cbranch_vccnz .LBB0_2742
	.p2align 6

.LBB0_3299:
	v_ashrrev_i32_e32 v53, 31, v52
	v_lshlrev_b64 v[54:55], 10, v[52:53]
	s_waitcnt vmcnt(3)
	v_lshl_add_u64 v[2:3], s[14:15], 0, v[54:55]
	v_lshl_add_u64 v[4:5], v[2:3], 0, v[48:49]
	global_load_dword v6, v[4:5], off
	global_load_dword v8, v[4:5], off offset:256
	v_lshl_add_u64 v[2:3], v[2:3], 0, v[46:47]
	global_load_dword v53, v[2:3], off
	global_load_dword v117, v[2:3], off offset:256
	global_load_dword v118, v[4:5], off offset:512
	global_load_dword v119, v[4:5], off offset:768
	v_cmp_lt_u32_e32 vcc, v116, v51
	v_mov_b32_e32 v128, 0
	v_mov_b32_e32 v127, 0
	s_waitcnt vmcnt(5)
	v_ashrrev_i32_e32 v7, 31, v6
	s_waitcnt vmcnt(4)
	v_ashrrev_i32_e32 v9, 31, v8
	v_lshlrev_b64 v[2:3], 2, v[6:7]
	v_lshlrev_b64 v[4:5], 2, v[8:9]
	v_lshl_add_u64 v[6:7], s[16:17], 0, v[2:3]
	v_lshl_add_u64 v[8:9], s[16:17], 0, v[4:5]
	v_lshl_add_u64 v[2:3], s[18:19], 0, v[2:3]
	v_lshl_add_u64 v[4:5], s[18:19], 0, v[4:5]
	global_load_dword v122, v[6:7], off
	global_load_dword v1, v[8:9], off
	global_load_dword v120, v[2:3], off
	global_load_dword v121, v[4:5], off
	s_and_saveexec_b64 s[24:25], vcc
	s_cbranch_execz .LBB0_3303
	v_lshl_add_u64 v[2:3], v[54:55], 1, v[34:35]
	global_load_dwordx4 v[6:9], v[2:3], off
	global_load_dwordx4 v[14:17], v[2:3], off offset:16
	v_cmp_lt_i32_e64 s[10:11], v111, v112
	v_lshrrev_b32_e32 v123, 4, v116
	v_mov_b32_e32 v128, 0
	v_cndmask_b32_e64 v2, v110, v111, s[10:11]
	v_cmp_lt_i32_e64 s[10:11], v113, v112
	s_mov_b64 s[26:27], 0
	v_mov_b32_e32 v127, 0
	v_cndmask_b32_e64 v3, v110, v113, s[10:11]
	v_lshlrev_b32_e32 v124, 2, v2
	v_lshlrev_b32_e32 v125, 2, v3
	v_mov_b32_e32 v126, v116
	s_waitcnt vmcnt(1)
	v_lshlrev_b32_e32 v2, 16, v6
	v_and_b32_e32 v3, 0xffff0000, v6
	v_lshlrev_b32_e32 v4, 16, v7
	v_and_b32_e32 v5, 0xffff0000, v7
	v_lshlrev_b32_e32 v6, 16, v8
	v_and_b32_e32 v7, 0xffff0000, v8
	v_lshlrev_b32_e32 v8, 16, v9
	v_and_b32_e32 v9, 0xffff0000, v9
	s_waitcnt vmcnt(0)
	v_lshlrev_b32_e32 v10, 16, v14
	v_and_b32_e32 v11, 0xffff0000, v14
	v_lshlrev_b32_e32 v12, 16, v15
	v_and_b32_e32 v13, 0xffff0000, v15
	v_lshlrev_b32_e32 v14, 16, v16
	v_and_b32_e32 v15, 0xffff0000, v16
	v_lshlrev_b32_e32 v16, 16, v17
	v_and_b32_e32 v17, 0xffff0000, v17
	.p2align 6

.LBB0_3309:
	s_andn2_saveexec_b64 s[10:11], s[12:13]
	v_mul_f32_e32 v1, v60, v60
	v_fmamk_f32 v2, v1, 0xba1345e1, v41
	v_fmaak_f32 v2, v1, v2, 0xbcdac9b8
	v_fmaak_f32 v2, v1, v2, 0x3de703be
	v_fmaak_f32 v2, v1, v2, 0xbec09330
	v_fmaak_f32 v1, v1, v2, 0x3e0375d0
	v_fma_f32 v61, |v60|, v1, |v60|
	s_or_b64 exec, exec, s[10:11]
	v_mov_b32_e32 v14, v0
	v_mov_b32_e32 v15, v0
	v_mov_b32_e32 v1, v0
	v_mov_b32_e32 v2, v0
	v_mov_b32_e32 v3, v0
	v_mov_b32_e32 v4, v0
	v_mov_b32_e32 v5, v0
	v_mov_b32_e32 v6, v0
	v_mov_b32_e32 v7, v0
	v_mov_b32_e32 v8, v0
	v_mov_b32_e32 v9, v0
	v_mov_b32_e32 v10, v0
	v_mov_b32_e32 v11, v0
	v_mov_b32_e32 v12, v0
	v_mov_b32_e32 v13, v0
	v_mov_b32_e32 v17, 0
	v_mov_b64_e32 v[32:33], v[14:15]
	v_mov_b32_e32 v16, v17
	v_mov_b64_e32 v[30:31], v[12:13]
	v_mov_b64_e32 v[28:29], v[10:11]
	v_mov_b64_e32 v[26:27], v[8:9]
	v_mov_b64_e32 v[24:25], v[6:7]
	v_mov_b64_e32 v[22:23], v[4:5]
	v_mov_b64_e32 v[20:21], v[2:3]
	v_mov_b64_e32 v[18:19], v[0:1]
	s_and_saveexec_b64 s[10:11], vcc
	s_cbranch_execz .LBB0_3316
	v_bfi_b32 v2, s43, v61, v60
	v_mul_f32_e32 v1, 0.5, v59
	v_add_f32_e32 v2, 1.0, v2
	v_bfi_b32 v3, s43, v58, v57
	v_mul_f32_e32 v1, v1, v2
	v_mul_f32_e32 v2, 0.5, v56
	v_add_f32_e32 v3, 1.0, v3
	v_mul_f32_e32 v2, v2, v3
	v_mul_f32_e32 v1, v119, v1
	v_mul_f32_e32 v2, v118, v2
	v_mov_b32_e32 v16, 0
	s_waitcnt vmcnt(0)
	v_mul_f32_e32 v1, v121, v1
	v_mul_f32_e32 v118, v120, v2
	s_mov_b64 s[12:13], 0
	v_mov_b32_e32 v17, v16
	v_mov_b32_e32 v2, v16
	v_mov_b32_e32 v3, v16
	v_mov_b32_e32 v4, v16
	v_mov_b32_e32 v5, v16
	v_mov_b32_e32 v6, v16
	v_mov_b32_e32 v7, v16
	v_mov_b32_e32 v8, v16
	v_mov_b32_e32 v9, v16
	v_mov_b32_e32 v10, v16
	v_mov_b32_e32 v11, v16
	v_mov_b32_e32 v12, v16
	v_mov_b32_e32 v13, v16
	v_mov_b32_e32 v14, v16
	v_mov_b32_e32 v15, v16
	.p2align 6
